# prio raise window variant qk (waves 4-7) + S2 hand schedule + ccdma + P0 transposes MLP
# speedup vs baseline: 1.0224x; 1.0224x over previous
; #define MFMA32(a, b, c) __builtin_amdgcn_mfma_f32_32x32x16_bf16((a), (b), (c), 0, 0, 0)
; DI void attn_unit(const Params& p, int bh, int qb, char* lds, float lam, int tid, int lane, int wid, const bool build_tab) {
;     ...
;             const lds_cptr kp = (lds_cptr)lds + sc + map * 8192 + hi * 1024 + r32 * 16;
;             bf16x8 kf[8];
; #pragma unroll
;             for (int d0 = 0; d0 < 4; ++d0) {
;                 kf[2 * d0] = *(const __attribute__((address_space(3))) bf16x8*)(kp + d0 * 2048);
;                 kf[2 * d0 + 1] = *(const __attribute__((address_space(3))) bf16x8*)(kp + d0 * 2048 + 512);
;             }
;             f32x16 s0 = cinit, s1 = cinit;
; #pragma unroll
;             for (int d0 = 0; d0 < 4; ++d0) { s0 = MFMA32(kf[2 * d0], qf[d0], s0); s1 = MFMA32(kf[2 * d0 + 1], qf[d0], s1); }
.Lp3_1:
	s_add_i32 s50, s84, 0
	s_add_i32 s51, s50, s61
	v_add3_u32 v136, s51, v204, v205
	ds_read_b128 v[80:83], v136
	ds_read_b128 v[128:131], v136 offset:512
	s_cmp_lt_u32 s7, s79
	s_waitcnt lgkmcnt(1)
	v_mfma_f32_32x32x16_bf16 v[96:111], v[80:83], v[112:115], v[64:79]
	s_waitcnt lgkmcnt(0)
	v_mfma_f32_32x32x16_bf16 v[80:95], v[128:131], v[112:115], v[64:79]
	ds_read_b128 v[128:131], v136 offset:2048
	ds_read_b128 v[132:135], v136 offset:2560
	s_waitcnt lgkmcnt(1)
	v_mfma_f32_32x32x16_bf16 v[96:111], v[128:131], v[116:119], v[96:111]
	s_waitcnt lgkmcnt(0)
	v_mfma_f32_32x32x16_bf16 v[80:95], v[132:135], v[116:119], v[80:95]
	ds_read_b128 v[128:131], v136 offset:4096
	ds_read_b128 v[132:135], v136 offset:4608
	ds_read_b128 v[222:225], v136 offset:6656
	s_waitcnt lgkmcnt(2)
	v_mfma_f32_32x32x16_bf16 v[96:111], v[128:131], v[120:123], v[96:111]
	ds_read_b128 v[128:131], v136 offset:6144
	s_waitcnt lgkmcnt(2)
	v_mfma_f32_32x32x16_bf16 v[80:95], v[132:135], v[120:123], v[80:95]
	v_add3_u32 v132, s50, v171, v202
	v_add_u32_e32 v220, v132, v203
	s_waitcnt lgkmcnt(0)
	v_mfma_f32_32x32x16_bf16 v[96:111], v[128:131], v[124:127], v[96:111]
	ds_read_b64_tr_b16 v[140:141], v220 offset:16384
	ds_read_b64_tr_b16 v[142:143], v220 offset:16896
	ds_read_b64_tr_b16 v[136:137], v220 offset:20480
	ds_read_b64_tr_b16 v[138:139], v220 offset:20992
	ds_read_b64_tr_b16 v[132:133], v220 offset:24576
	ds_read_b64_tr_b16 v[134:135], v220 offset:25088
	ds_read_b64_tr_b16 v[128:129], v220 offset:28672
	ds_read_b64_tr_b16 v[130:131], v220 offset:29184
	v_mfma_f32_32x32x16_bf16 v[80:95], v[222:225], v[124:127], v[80:95]
	s_setprio 0
	s_cbranch_scc1 .LBB0_355
	v_add_u32_e32 v221, s83, v219
	v_add_u32_e32 v222, 0x18600, v221
	v_add_u32_e32 v224, 0x18680, v221
	v_add_u32_e32 v226, 0x18608, v221
	v_add_u32_e32 v228, 0x18688, v221
	v_add_u32_e32 v230, 0x18620, v221
	v_add_u32_e32 v232, 0x186a0, v221
	v_add_u32_e32 v234, 0x18628, v221
	v_add_u32_e32 v236, 0x186a8, v221
	v_add_u32_e32 v238, 0x18640, v221
	v_add_u32_e32 v240, 0x186c0, v221
	v_add_u32_e32 v242, 0x18648, v221
	v_add_u32_e32 v244, 0x186c8, v221
	v_add_u32_e32 v248, 0x18660, v221
	v_add_u32_e32 v250, 0x186e0, v221
	v_add_u32_e32 v246, 0x18668, v221
	ds_read2_b32 v[222:223], v222 offset1:1
	ds_read2_b32 v[224:225], v224 offset1:1
	ds_read2_b32 v[226:227], v226 offset1:1
	ds_read2_b32 v[228:229], v228 offset1:1
	ds_read2_b32 v[230:231], v230 offset1:1
	ds_read2_b32 v[232:233], v232 offset1:1
	ds_read2_b32 v[234:235], v234 offset1:1
	ds_read2_b32 v[236:237], v236 offset1:1
	ds_read2_b32 v[238:239], v238 offset1:1
	ds_read2_b32 v[240:241], v240 offset1:1
	ds_read2_b32 v[242:243], v242 offset1:1
	ds_read2_b32 v[244:245], v244 offset1:1
	ds_read2_b32 v[246:247], v246 offset1:1
	ds_read2_b32 v[248:249], v248 offset1:1
	v_add_u32_e32 v221, 0x186e8, v221
	ds_read2_b32 v[250:251], v250 offset1:1
	ds_read2_b32 v[252:253], v221 offset1:1
	s_waitcnt lgkmcnt(5)
	v_pk_add_f32 v[106:107], v[106:107], v[242:243]
	s_waitcnt lgkmcnt(3)
	v_pk_add_f32 v[110:111], v[110:111], v[246:247]
	s_waitcnt lgkmcnt(2)
	v_pk_add_f32 v[108:109], v[108:109], v[248:249]
	v_pk_add_f32 v[104:105], v[104:105], v[238:239]
	v_pk_add_f32 v[102:103], v[102:103], v[234:235]
	v_pk_add_f32 v[100:101], v[100:101], v[230:231]
	v_pk_add_f32 v[98:99], v[98:99], v[226:227]
	v_pk_add_f32 v[96:97], v[96:97], v[222:223]
	s_waitcnt lgkmcnt(0)
	v_pk_add_f32 v[94:95], v[94:95], v[252:253]
	v_pk_add_f32 v[92:93], v[92:93], v[250:251]
	v_pk_add_f32 v[90:91], v[90:91], v[244:245]
	v_pk_add_f32 v[88:89], v[88:89], v[240:241]
	v_pk_add_f32 v[86:87], v[86:87], v[236:237]
	v_pk_add_f32 v[84:85], v[84:85], v[232:233]
	v_pk_add_f32 v[82:83], v[82:83], v[228:229]
	v_pk_add_f32 v[80:81], v[80:81], v[224:225]

; #define MFMA32(a, b, c) __builtin_amdgcn_mfma_f32_32x32x16_bf16((a), (b), (c), 0, 0, 0)
; DI void attn_unit(const Params& p, int bh, int qb, char* lds, float lam, int tid, int lane, int wid, const bool build_tab) {
;     ...
;             const lds_cptr kp = (lds_cptr)lds + sc + map * 8192 + hi * 1024 + r32 * 16;
;             bf16x8 kf[8];
; #pragma unroll
;             for (int d0 = 0; d0 < 4; ++d0) {
;                 kf[2 * d0] = *(const __attribute__((address_space(3))) bf16x8*)(kp + d0 * 2048);
;                 kf[2 * d0 + 1] = *(const __attribute__((address_space(3))) bf16x8*)(kp + d0 * 2048 + 512);
;             }
;             f32x16 s0 = cinit, s1 = cinit;
; #pragma unroll
;             for (int d0 = 0; d0 < 4; ++d0) { s0 = MFMA32(kf[2 * d0], qf[d0], s0); s1 = MFMA32(kf[2 * d0 + 1], qf[d0], s1); }
.Lp3_0:
	s_add_i32 s52, s70, 0
	s_add_i32 s53, s52, s61
	v_add3_u32 v136, s53, v204, v205
	ds_read_b128 v[80:83], v136
	ds_read_b128 v[128:131], v136 offset:512
	s_cmp_lt_i32 s51, s57
	s_waitcnt lgkmcnt(1)
	v_mfma_f32_32x32x16_bf16 v[96:111], v[80:83], v[112:115], v[64:79]
	s_waitcnt lgkmcnt(0)
	v_mfma_f32_32x32x16_bf16 v[80:95], v[128:131], v[112:115], v[64:79]
	ds_read_b128 v[128:131], v136 offset:2048
	ds_read_b128 v[132:135], v136 offset:2560
	s_waitcnt lgkmcnt(1)
	v_mfma_f32_32x32x16_bf16 v[96:111], v[128:131], v[116:119], v[96:111]
	s_waitcnt lgkmcnt(0)
	v_mfma_f32_32x32x16_bf16 v[80:95], v[132:135], v[116:119], v[80:95]
	ds_read_b128 v[128:131], v136 offset:4096
	ds_read_b128 v[132:135], v136 offset:4608
	ds_read_b128 v[178:181], v136 offset:6656
	s_waitcnt lgkmcnt(2)
	v_mfma_f32_32x32x16_bf16 v[96:111], v[128:131], v[120:123], v[96:111]
	ds_read_b128 v[128:131], v136 offset:6144
	s_waitcnt lgkmcnt(2)
	v_mfma_f32_32x32x16_bf16 v[80:95], v[132:135], v[120:123], v[80:95]
	v_add3_u32 v132, s52, v171, v202
	v_add_u32_e32 v177, v132, v203
	s_waitcnt lgkmcnt(0)
	v_mfma_f32_32x32x16_bf16 v[96:111], v[128:131], v[124:127], v[96:111]
	ds_read_b64_tr_b16 v[140:141], v177 offset:16384
	ds_read_b64_tr_b16 v[142:143], v177 offset:16896
	ds_read_b64_tr_b16 v[136:137], v177 offset:20480
	ds_read_b64_tr_b16 v[138:139], v177 offset:20992
	ds_read_b64_tr_b16 v[132:133], v177 offset:24576
	ds_read_b64_tr_b16 v[134:135], v177 offset:25088
	ds_read_b64_tr_b16 v[128:129], v177 offset:28672
	ds_read_b64_tr_b16 v[130:131], v177 offset:29184
	v_mfma_f32_32x32x16_bf16 v[80:95], v[178:181], v[124:127], v[80:95]
	s_setprio 0
	s_cbranch_scc1 .LBB0_375
	v_add_u32_e32 v219, s69, v146
	v_add_u32_e32 v178, 0x18600, v219
	v_add_u32_e32 v180, 0x18680, v219
	v_add_u32_e32 v182, 0x18608, v219
	v_add_u32_e32 v184, 0x18688, v219
	v_add_u32_e32 v186, 0x18620, v219
	v_add_u32_e32 v188, 0x186a0, v219
	v_add_u32_e32 v190, 0x18628, v219
	v_add_u32_e32 v192, 0x186a8, v219
	v_add_u32_e32 v194, 0x18640, v219
	v_add_u32_e32 v196, 0x186c0, v219
	v_add_u32_e32 v198, 0x18648, v219
	v_add_u32_e32 v220, 0x186c8, v219
	v_add_u32_e32 v224, 0x18660, v219
	v_add_u32_e32 v226, 0x186e0, v219
	v_add_u32_e32 v222, 0x18668, v219
	ds_read2_b32 v[178:179], v178 offset1:1
	ds_read2_b32 v[180:181], v180 offset1:1
	ds_read2_b32 v[182:183], v182 offset1:1
	ds_read2_b32 v[184:185], v184 offset1:1
	ds_read2_b32 v[186:187], v186 offset1:1
	ds_read2_b32 v[188:189], v188 offset1:1
	ds_read2_b32 v[190:191], v190 offset1:1
	ds_read2_b32 v[192:193], v192 offset1:1
	ds_read2_b32 v[194:195], v194 offset1:1
	ds_read2_b32 v[196:197], v196 offset1:1
	ds_read2_b32 v[198:199], v198 offset1:1
	ds_read2_b32 v[220:221], v220 offset1:1
	ds_read2_b32 v[222:223], v222 offset1:1
	ds_read2_b32 v[224:225], v224 offset1:1
	v_add_u32_e32 v219, 0x186e8, v219
	ds_read2_b32 v[226:227], v226 offset1:1
	ds_read2_b32 v[228:229], v219 offset1:1
	s_waitcnt lgkmcnt(5)
	v_pk_add_f32 v[106:107], v[106:107], v[198:199]
	s_waitcnt lgkmcnt(3)
	v_pk_add_f32 v[110:111], v[110:111], v[222:223]
	s_waitcnt lgkmcnt(2)
	v_pk_add_f32 v[108:109], v[108:109], v[224:225]
	v_pk_add_f32 v[104:105], v[104:105], v[194:195]
	v_pk_add_f32 v[102:103], v[102:103], v[190:191]
	v_pk_add_f32 v[100:101], v[100:101], v[186:187]
	v_pk_add_f32 v[98:99], v[98:99], v[182:183]
	v_pk_add_f32 v[96:97], v[96:97], v[178:179]
	s_waitcnt lgkmcnt(0)
	v_pk_add_f32 v[94:95], v[94:95], v[228:229]
	v_pk_add_f32 v[92:93], v[92:93], v[226:227]
	v_pk_add_f32 v[90:91], v[90:91], v[220:221]
	v_pk_add_f32 v[88:89], v[88:89], v[196:197]
	v_pk_add_f32 v[86:87], v[86:87], v[192:193]
	v_pk_add_f32 v[84:85], v[84:85], v[188:189]
	v_pk_add_f32 v[82:83], v[82:83], v[184:185]
	v_pk_add_f32 v[80:81], v[80:81], v[180:181]
